# helper B rewritten from scratch: deep-pipelined down2 conversion (loads of tile j+2 issued as soon as tile j is in LDS, saddr addressing), 10240 tiles in P8 idle window; helper A 7168 as before
# speedup vs baseline: 1.0019x; 1.0019x over previous
; __global__ void __launch_bounds__(NWAVES * 64, 2) fwd(Args args) {
;     ...
;           for (;;) {
;             __syncthreads();
;             if (tid == 0) MISC[16] = qpre;
;             __syncthreads();
;             constexpr int NB64 = (NCB * 3) / 4, NB16 = (NCB - NB64) * 4;
;             const unsigned q = MISC[16]; if (q >= 512u + (DEFER_AT == 5 ? (unsigned)(NB64 + NB16) : 0u)) break;
.LBB0_643:
	s_or_b64 exec, exec, s[2:3]
	s_waitcnt lgkmcnt(0)
	s_barrier
	ds_read_b32 v0, v164
	s_movk_i32 s2, 0x556
	s_waitcnt lgkmcnt(0)
	v_cmp_lt_u32_e64 s[2:3], s2, v0
	v_readfirstlane_b32 s25, v0
	s_and_b64 vcc, exec, s[2:3]
	s_cbranch_vccnz .LBB0_640
	s_and_saveexec_b64 s[6:7], s[4:5]
	s_cbranch_execz .LBB0_646
	v_mov_b32_e32 v0, v161
	s_nop 0
	v_ashrrev_i32_e32 v1, 31, v0
	v_lshl_add_u64 v[0:1], v[0:1], 2, s[44:45]
	global_atomic_add v162, v[0:1], v165, off sc0

; __global__ void __launch_bounds__(NWAVES * 64, 2) fwd(Args args) {
;     ...
;             if (!conv) attn_wg(PROJ, CONCAT, idx, L, tid, lane, wave);
;             else {
;                 const bool small = idx >= NB64; const int first = NI0 + (small ? NB64 * 64 + (idx - NB64) * 16 : idx * 64) + wave;
;                 f32x4 va[16], vb[16]; P0T_DECL(a); P0T_DECL(b);
.LBB0_679:
	s_and_b64 vcc, exec, s[4:5]
	s_cbranch_vccz .LBB0_640
	s_add_i32 s4, s25, 0xfffffe00
	s_lshl_b32 s58, s4, 4
	s_addk_i32 s58, 0x3390
	s_lshl_b32 s42, s4, 6
	s_cmpk_gt_u32 s4, 0x112
	s_cselect_b32 s5, s58, s42
	s_add_i32 s25, s86, s5
	s_cmpk_lt_u32 s4, 0x113
	s_mov_b64 s[4:5], -1
	s_cbranch_scc0 .LBB0_882
	s_add_i32 s42, s42, s28
	s_cmpk_gt_u32 s42, 0xfff
	s_cbranch_scc0 .LBB0_685
	s_cmpk_gt_u32 s42, 0x65ff
	s_cbranch_scc0 .LBB0_942
	s_and_b32 s4, s42, 0x7ffffc0
	s_add_i32 s64, s4, 0xffff9a00
	s_mov_b64 s[70:71], 0
	s_cbranch_execz .LBB0_943

; #define LAS __attribute__((address_space(3)))
; __device__ __forceinline__ unsigned pk2(float lo, float hi) { return pg8::cvt_pk_bf16(lo, hi); }
; __device__ __forceinline__ void p0_load(const float* W, int N, int k0, int n0, int lane, f32x4 (&v)[16]) {
;     const int c = lane & 15, rq = lane >> 4;
;     int col = n0 + 4 * c; col = col < N - 4 ? col : N - 4;
;     const float* p = W + (size_t)(k0 + rq) * N + col;
; #pragma unroll
;     for (int j = 0; j < 16; ++j) v[j] = __builtin_nontemporal_load((const f32x4*)(p + (size_t)(4 * j) * N));
; }
; __device__ __forceinline__ void p0_finish(bf16* WT, const float* gain, int N, int k0, int n0, int ldw, int blk, int off, int lane, const f32x4 (&v)[16], LAS float* scr) {
;     const int c = lane & 15, rq = lane >> 4, c8 = lane & 7;
;     f32x4 g0 = {1.f, 1.f, 1.f, 1.f}, g1 = g0;
;     if (gain) { g0 = *(const f32x4*)(gain + k0 + 8 * c8); g1 = *(const f32x4*)(gain + k0 + 8 * c8 + 4); }
; #pragma unroll
;     for (int j = 0; j < 16; ++j) { LAS float* s = scr + (4 * j + rq) * 65 + 4 * c; s[0] = v[j][0]; s[1] = v[j][1]; s[2] = v[j][2]; s[3] = v[j][3]; }
;     asm volatile("s_waitcnt lgkmcnt(0)" ::: "memory");
; #pragma unroll
;     for (int jj = 0; jj < 8; ++jj) { const int n = (lane >> 3) + 8 * jj; const LAS float* s = scr + (8 * c8) * 65 + n;
;         u32x4 o; o.x = pk2(s[0 * 65] * g0[0], s[1 * 65] * g0[1]); o.y = pk2(s[2 * 65] * g0[2], s[3 * 65] * g0[3]); o.z = pk2(s[4 * 65] * g1[0], s[5 * 65] * g1[1]); o.w = pk2(s[6 * 65] * g1[2], s[7 * 65] * g1[3]);
;         const int ng = n0 + n;
;         if (ng < N) { const int row = (ng >> 7) * blk + (ng & 127) + off; __builtin_nontemporal_store(o, (u32x4*)(WT + (size_t)row * ldw + k0 + 8 * c8)); } }
;     asm volatile("s_waitcnt lgkmcnt(0)" ::: "memory");
; }
.LBB0_1140:
	s_cmpk_lt_u32 s8, 0xc0
	s_cbranch_scc1 .Lhn_done
	v_writelane_b32 v238, s0, 0
	v_writelane_b32 v238, s1, 1
	v_writelane_b32 v238, s2, 2
	v_writelane_b32 v238, s3, 3
	v_writelane_b32 v238, s4, 4
	v_writelane_b32 v238, s5, 5
	v_writelane_b32 v238, s6, 6
	v_writelane_b32 v238, s7, 7
	v_writelane_b32 v238, s8, 8
	v_writelane_b32 v238, s9, 9
	v_writelane_b32 v238, s10, 10
	v_writelane_b32 v238, s11, 11
	v_writelane_b32 v238, s12, 12
	v_writelane_b32 v238, s13, 13
	v_writelane_b32 v238, s14, 14
	v_writelane_b32 v238, s15, 15
	v_writelane_b32 v238, s16, 16
	v_writelane_b32 v238, s17, 17
	v_writelane_b32 v238, s18, 18
	v_writelane_b32 v238, s19, 19
	v_writelane_b32 v238, s20, 20
	v_writelane_b32 v238, s21, 21
	v_writelane_b32 v238, s22, 22
	v_writelane_b32 v238, s23, 23
	v_writelane_b32 v238, s24, 24
	v_writelane_b32 v238, s25, 25
	v_writelane_b32 v238, s26, 26
	v_writelane_b32 v238, s27, 27
	v_writelane_b32 v238, s28, 28
	v_writelane_b32 v238, s29, 29
	v_writelane_b32 v238, s30, 30
	v_writelane_b32 v238, s31, 31
	v_writelane_b32 v238, s32, 32
	v_writelane_b32 v238, s33, 33
	v_writelane_b32 v238, s34, 34
	v_writelane_b32 v238, s35, 35
	v_writelane_b32 v238, s36, 36
	v_writelane_b32 v238, s37, 37
	v_writelane_b32 v238, s38, 38
	v_writelane_b32 v238, s39, 39
	v_writelane_b32 v238, s40, 40
	v_writelane_b32 v238, s41, 41
	v_writelane_b32 v238, s42, 42
	v_writelane_b32 v238, s43, 43
	v_writelane_b32 v238, s44, 44
	v_writelane_b32 v238, s45, 45
	v_writelane_b32 v238, s46, 46
	v_writelane_b32 v238, s47, 47
	v_writelane_b32 v238, s48, 48
	v_writelane_b32 v238, s49, 49
	v_writelane_b32 v238, s50, 50
	v_writelane_b32 v238, s51, 51
	v_writelane_b32 v238, s52, 52
	v_writelane_b32 v238, s53, 53
	v_writelane_b32 v238, s54, 54
	v_writelane_b32 v238, s55, 55
	v_writelane_b32 v238, s56, 56
	v_writelane_b32 v238, s57, 57
	v_writelane_b32 v238, s58, 58
	v_writelane_b32 v238, s59, 59
	v_writelane_b32 v238, s60, 60
	v_writelane_b32 v238, s61, 61
	v_writelane_b32 v238, s62, 62
	v_writelane_b32 v238, s63, 63
	v_writelane_b32 v239, s64, 0
	v_writelane_b32 v239, s65, 1
	v_writelane_b32 v239, s66, 2
	v_writelane_b32 v239, s67, 3
	v_writelane_b32 v239, s68, 4
	v_writelane_b32 v239, s69, 5
	v_writelane_b32 v239, s70, 6
	v_writelane_b32 v239, s71, 7
	v_writelane_b32 v239, s72, 8
	v_writelane_b32 v239, s73, 9
	v_writelane_b32 v239, s74, 10
	v_writelane_b32 v239, s75, 11
	v_writelane_b32 v239, s76, 12
	v_writelane_b32 v239, s77, 13
	v_writelane_b32 v239, s78, 14
	v_writelane_b32 v239, s79, 15
	v_writelane_b32 v239, s80, 16
	v_writelane_b32 v239, s81, 17
	v_writelane_b32 v239, s82, 18
	v_writelane_b32 v239, s83, 19
	v_writelane_b32 v239, s84, 20
	v_writelane_b32 v239, s85, 21
	v_writelane_b32 v239, s86, 22
	v_writelane_b32 v239, s87, 23
	v_writelane_b32 v239, s88, 24
	v_writelane_b32 v239, s89, 25
	v_writelane_b32 v239, s90, 26
	v_writelane_b32 v239, s91, 27
	v_writelane_b32 v239, s92, 28
	v_writelane_b32 v239, s93, 29
	v_writelane_b32 v239, s94, 30
	v_writelane_b32 v239, s95, 31
	v_writelane_b32 v239, s96, 32
	v_writelane_b32 v239, s97, 33
	v_writelane_b32 v239, s98, 34
	v_writelane_b32 v239, s99, 35
	v_writelane_b32 v239, s100, 36
	v_writelane_b32 v239, s101, 37
	v_writelane_b32 v239, vcc_lo, 38
	v_writelane_b32 v239, vcc_hi, 39
	v_writelane_b32 v239, m0, 40
	s_add_i32 s16, s8, 0xffffff40
	s_lshl_b32 s16, s16, 3
	s_add_i32 s16, s16, s28
	s_load_dwordx2 s[30:31], s[0:1], 0x78
	v_mbcnt_lo_u32_b32 v146, -1, 0
	v_mbcnt_hi_u32_b32 v146, -1, v146
	s_and_b32 s17, s16, 63
	s_lshr_b32 s18, s16, 6
	s_add_i32 s18, s18, 12
	s_mul_i32 s19, s28, 0x4100
	v_lshrrev_b32_e32 v131, 4, v146
	v_and_b32_e32 v133, 15, v146
	v_mul_u32_u24_e32 v128, 0x104, v131
	v_lshl_add_u32 v128, v133, 4, v128
	v_add_u32_e32 v128, s19, v128
	v_lshlrev_b32_e32 v131, 14, v131
	v_lshl_add_u32 v131, v133, 4, v131
	v_and_b32_e32 v133, 7, v146
	v_lshrrev_b32_e32 v132, 3, v146
	v_mul_u32_u24_e32 v129, 0x820, v133
	v_lshl_add_u32 v129, v132, 2, v129
	v_add_u32_e32 v129, s19, v129
	v_add_u32_e32 v130, 0x400, v129
	v_mul_u32_u24_e32 v132, 0x5680, v132
	v_lshl_add_u32 v132, v133, 4, v132
	s_waitcnt lgkmcnt(0)
	s_lshl_b32 s2, s17, 8
	s_add_u32 s20, s30, s2
	s_addc_u32 s21, s31, 0
	s_lshr_b32 s3, s18, 12
	s_lshl_b32 s2, s18, 20
	s_add_u32 s20, s20, s2
	s_addc_u32 s21, s21, s3
	s_add_u32 s22, s14, 0x25000000
	s_addc_u32 s23, s15, 0
	s_mul_i32 s2, s17, 0x15a000
	s_add_u32 s22, s22, s2
	s_addc_u32 s23, s23, 0
	s_lshl_b32 s2, s18, 7
	s_add_u32 s22, s22, s2
	s_addc_u32 s23, s23, 0
	s_mov_b32 s26, 0
	s_mov_b32 s27, 1
	global_load_dwordx4 v[0:3], v131, s[20:21] nt
	s_add_u32 s24, s20, 0x10000
	s_addc_u32 s25, s21, 0
	global_load_dwordx4 v[4:7], v131, s[24:25] nt
	s_add_u32 s24, s20, 0x20000
	s_addc_u32 s25, s21, 0
	global_load_dwordx4 v[8:11], v131, s[24:25] nt
	s_add_u32 s24, s20, 0x30000
	s_addc_u32 s25, s21, 0
	global_load_dwordx4 v[12:15], v131, s[24:25] nt
	s_add_u32 s24, s20, 0x40000
	s_addc_u32 s25, s21, 0
	global_load_dwordx4 v[16:19], v131, s[24:25] nt
	s_add_u32 s24, s20, 0x50000
	s_addc_u32 s25, s21, 0
	global_load_dwordx4 v[20:23], v131, s[24:25] nt
	s_add_u32 s24, s20, 0x60000
	s_addc_u32 s25, s21, 0
	global_load_dwordx4 v[24:27], v131, s[24:25] nt
	s_add_u32 s24, s20, 0x70000
	s_addc_u32 s25, s21, 0
	global_load_dwordx4 v[28:31], v131, s[24:25] nt
	s_add_u32 s24, s20, 0x80000
	s_addc_u32 s25, s21, 0
	global_load_dwordx4 v[32:35], v131, s[24:25] nt
	s_add_u32 s24, s20, 0x90000
	s_addc_u32 s25, s21, 0
	global_load_dwordx4 v[36:39], v131, s[24:25] nt
	s_add_u32 s24, s20, 0xa0000
	s_addc_u32 s25, s21, 0
	global_load_dwordx4 v[40:43], v131, s[24:25] nt
	s_add_u32 s24, s20, 0xb0000
	s_addc_u32 s25, s21, 0
; #define LAS __attribute__((address_space(3)))
; __device__ __forceinline__ unsigned pk2(float lo, float hi) { return pg8::cvt_pk_bf16(lo, hi); }
; __device__ __forceinline__ void p0_load(const float* W, int N, int k0, int n0, int lane, f32x4 (&v)[16]) {
;     const int c = lane & 15, rq = lane >> 4;
;     int col = n0 + 4 * c; col = col < N - 4 ? col : N - 4;
;     const float* p = W + (size_t)(k0 + rq) * N + col;
; #pragma unroll
;     for (int j = 0; j < 16; ++j) v[j] = __builtin_nontemporal_load((const f32x4*)(p + (size_t)(4 * j) * N));
; }
; __device__ __forceinline__ void p0_finish(bf16* WT, const float* gain, int N, int k0, int n0, int ldw, int blk, int off, int lane, const f32x4 (&v)[16], LAS float* scr) {
;     const int c = lane & 15, rq = lane >> 4, c8 = lane & 7;
;     f32x4 g0 = {1.f, 1.f, 1.f, 1.f}, g1 = g0;
;     if (gain) { g0 = *(const f32x4*)(gain + k0 + 8 * c8); g1 = *(const f32x4*)(gain + k0 + 8 * c8 + 4); }
; #pragma unroll
;     for (int j = 0; j < 16; ++j) { LAS float* s = scr + (4 * j + rq) * 65 + 4 * c; s[0] = v[j][0]; s[1] = v[j][1]; s[2] = v[j][2]; s[3] = v[j][3]; }
;     asm volatile("s_waitcnt lgkmcnt(0)" ::: "memory");
; #pragma unroll
;     for (int jj = 0; jj < 8; ++jj) { const int n = (lane >> 3) + 8 * jj; const LAS float* s = scr + (8 * c8) * 65 + n;
;         u32x4 o; o.x = pk2(s[0 * 65] * g0[0], s[1 * 65] * g0[1]); o.y = pk2(s[2 * 65] * g0[2], s[3 * 65] * g0[3]); o.z = pk2(s[4 * 65] * g1[0], s[5 * 65] * g1[1]); o.w = pk2(s[6 * 65] * g1[2], s[7 * 65] * g1[3]);
;         const int ng = n0 + n;
;         if (ng < N) { const int row = (ng >> 7) * blk + (ng & 127) + off; __builtin_nontemporal_store(o, (u32x4*)(WT + (size_t)row * ldw + k0 + 8 * c8)); } }
;     asm volatile("s_waitcnt lgkmcnt(0)" ::: "memory");
; }
	global_load_dwordx4 v[44:47], v131, s[24:25] nt
	s_add_u32 s24, s20, 0xc0000
	s_addc_u32 s25, s21, 0
	global_load_dwordx4 v[48:51], v131, s[24:25] nt
	s_add_u32 s24, s20, 0xd0000
	s_addc_u32 s25, s21, 0
	global_load_dwordx4 v[52:55], v131, s[24:25] nt
	s_add_u32 s24, s20, 0xe0000
	s_addc_u32 s25, s21, 0
	global_load_dwordx4 v[56:59], v131, s[24:25] nt
	s_add_u32 s24, s20, 0xf0000
	s_addc_u32 s25, s21, 0
	global_load_dwordx4 v[60:63], v131, s[24:25] nt
	s_cmp_lt_u32 s27, 20
	s_cselect_b32 s2, 0x800000, 0
	s_add_u32 s20, s20, s2
	s_addc_u32 s21, s21, 0
	s_add_i32 s27, s27, 1
	global_load_dwordx4 v[64:67], v131, s[20:21] nt
	s_add_u32 s24, s20, 0x10000
	s_addc_u32 s25, s21, 0
	global_load_dwordx4 v[68:71], v131, s[24:25] nt
	s_add_u32 s24, s20, 0x20000
	s_addc_u32 s25, s21, 0
	global_load_dwordx4 v[72:75], v131, s[24:25] nt
	s_add_u32 s24, s20, 0x30000
	s_addc_u32 s25, s21, 0
	global_load_dwordx4 v[76:79], v131, s[24:25] nt
	s_add_u32 s24, s20, 0x40000
	s_addc_u32 s25, s21, 0
	global_load_dwordx4 v[80:83], v131, s[24:25] nt
	s_add_u32 s24, s20, 0x50000
	s_addc_u32 s25, s21, 0
	global_load_dwordx4 v[84:87], v131, s[24:25] nt
	s_add_u32 s24, s20, 0x60000
	s_addc_u32 s25, s21, 0
	global_load_dwordx4 v[88:91], v131, s[24:25] nt
	s_add_u32 s24, s20, 0x70000
	s_addc_u32 s25, s21, 0
	global_load_dwordx4 v[92:95], v131, s[24:25] nt
	s_add_u32 s24, s20, 0x80000
	s_addc_u32 s25, s21, 0
	global_load_dwordx4 v[96:99], v131, s[24:25] nt
	s_add_u32 s24, s20, 0x90000
	s_addc_u32 s25, s21, 0
	global_load_dwordx4 v[100:103], v131, s[24:25] nt
	s_add_u32 s24, s20, 0xa0000
	s_addc_u32 s25, s21, 0
	global_load_dwordx4 v[104:107], v131, s[24:25] nt
	s_add_u32 s24, s20, 0xb0000
	s_addc_u32 s25, s21, 0
	global_load_dwordx4 v[108:111], v131, s[24:25] nt
	s_add_u32 s24, s20, 0xc0000
	s_addc_u32 s25, s21, 0
	global_load_dwordx4 v[112:115], v131, s[24:25] nt
	s_add_u32 s24, s20, 0xd0000
	s_addc_u32 s25, s21, 0
	global_load_dwordx4 v[116:119], v131, s[24:25] nt
	s_add_u32 s24, s20, 0xe0000
	s_addc_u32 s25, s21, 0
	global_load_dwordx4 v[120:123], v131, s[24:25] nt
	s_add_u32 s24, s20, 0xf0000
	s_addc_u32 s25, s21, 0
	global_load_dwordx4 v[124:127], v131, s[24:25] nt
.Lhn_loop:
	s_cmp_eq_u32 s26, 0
	s_cbranch_scc0 .Lhn_w0
	s_waitcnt vmcnt(16)
.Lhn_w0:
	s_waitcnt vmcnt(32)
	ds_write2_b32 v128, v0, v1 offset1:1
	ds_write2_b32 v128, v2, v3 offset0:2 offset1:3
	v_add_u32_e32 v133, 0x410, v128
	ds_write2_b32 v133, v4, v5 offset1:1
	ds_write2_b32 v133, v6, v7 offset0:2 offset1:3
	v_add_u32_e32 v147, 0x820, v128
	ds_write2_b32 v147, v8, v9 offset1:1
	ds_write2_b32 v147, v10, v11 offset0:2 offset1:3
	v_add_u32_e32 v133, 0xc30, v128
	ds_write2_b32 v133, v12, v13 offset1:1
	ds_write2_b32 v133, v14, v15 offset0:2 offset1:3
	v_add_u32_e32 v147, 0x1040, v128
	ds_write2_b32 v147, v16, v17 offset1:1
	ds_write2_b32 v147, v18, v19 offset0:2 offset1:3
	v_add_u32_e32 v133, 0x1450, v128
	ds_write2_b32 v133, v20, v21 offset1:1
	ds_write2_b32 v133, v22, v23 offset0:2 offset1:3
	v_add_u32_e32 v147, 0x1860, v128
	ds_write2_b32 v147, v24, v25 offset1:1
	ds_write2_b32 v147, v26, v27 offset0:2 offset1:3
	v_add_u32_e32 v133, 0x1c70, v128
	ds_write2_b32 v133, v28, v29 offset1:1
	ds_write2_b32 v133, v30, v31 offset0:2 offset1:3
	v_add_u32_e32 v147, 0x2080, v128
	ds_write2_b32 v147, v32, v33 offset1:1
	ds_write2_b32 v147, v34, v35 offset0:2 offset1:3
	v_add_u32_e32 v133, 0x2490, v128
	ds_write2_b32 v133, v36, v37 offset1:1
	ds_write2_b32 v133, v38, v39 offset0:2 offset1:3
	v_add_u32_e32 v147, 0x28a0, v128
	ds_write2_b32 v147, v40, v41 offset1:1
	ds_write2_b32 v147, v42, v43 offset0:2 offset1:3
	v_add_u32_e32 v133, 0x2cb0, v128
	ds_write2_b32 v133, v44, v45 offset1:1
	ds_write2_b32 v133, v46, v47 offset0:2 offset1:3
	v_add_u32_e32 v147, 0x30c0, v128
	ds_write2_b32 v147, v48, v49 offset1:1
	ds_write2_b32 v147, v50, v51 offset0:2 offset1:3
	v_add_u32_e32 v133, 0x34d0, v128
	ds_write2_b32 v133, v52, v53 offset1:1
	ds_write2_b32 v133, v54, v55 offset0:2 offset1:3
	v_add_u32_e32 v147, 0x38e0, v128
	ds_write2_b32 v147, v56, v57 offset1:1
	ds_write2_b32 v147, v58, v59 offset0:2 offset1:3
	v_add_u32_e32 v133, 0x3cf0, v128
	ds_write2_b32 v133, v60, v61 offset1:1
	ds_write2_b32 v133, v62, v63 offset0:2 offset1:3
	s_waitcnt lgkmcnt(0)
	s_cmp_lt_u32 s27, 20
	s_cselect_b32 s2, 0x800000, 0
	s_add_u32 s20, s20, s2
	s_addc_u32 s21, s21, 0
	s_add_i32 s27, s27, 1
	global_load_dwordx4 v[0:3], v131, s[20:21] nt
	s_add_u32 s24, s20, 0x10000
	s_addc_u32 s25, s21, 0
	global_load_dwordx4 v[4:7], v131, s[24:25] nt
	s_add_u32 s24, s20, 0x20000
	s_addc_u32 s25, s21, 0
	global_load_dwordx4 v[8:11], v131, s[24:25] nt
	s_add_u32 s24, s20, 0x30000
	s_addc_u32 s25, s21, 0
	global_load_dwordx4 v[12:15], v131, s[24:25] nt
	s_add_u32 s24, s20, 0x40000
	s_addc_u32 s25, s21, 0
	global_load_dwordx4 v[16:19], v131, s[24:25] nt
	s_add_u32 s24, s20, 0x50000
	s_addc_u32 s25, s21, 0
	global_load_dwordx4 v[20:23], v131, s[24:25] nt
	s_add_u32 s24, s20, 0x60000
	s_addc_u32 s25, s21, 0
	global_load_dwordx4 v[24:27], v131, s[24:25] nt
	s_add_u32 s24, s20, 0x70000
	s_addc_u32 s25, s21, 0
	global_load_dwordx4 v[28:31], v131, s[24:25] nt
	s_add_u32 s24, s20, 0x80000
	s_addc_u32 s25, s21, 0
	global_load_dwordx4 v[32:35], v131, s[24:25] nt
	s_add_u32 s24, s20, 0x90000
	s_addc_u32 s25, s21, 0
	global_load_dwordx4 v[36:39], v131, s[24:25] nt
	s_add_u32 s24, s20, 0xa0000
	s_addc_u32 s25, s21, 0
	global_load_dwordx4 v[40:43], v131, s[24:25] nt
	s_add_u32 s24, s20, 0xb0000
	s_addc_u32 s25, s21, 0
	global_load_dwordx4 v[44:47], v131, s[24:25] nt
	s_add_u32 s24, s20, 0xc0000
	s_addc_u32 s25, s21, 0
	global_load_dwordx4 v[48:51], v131, s[24:25] nt
	s_add_u32 s24, s20, 0xd0000
	s_addc_u32 s25, s21, 0
	global_load_dwordx4 v[52:55], v131, s[24:25] nt
	s_add_u32 s24, s20, 0xe0000
	s_addc_u32 s25, s21, 0
	global_load_dwordx4 v[56:59], v131, s[24:25] nt
	s_add_u32 s24, s20, 0xf0000
	s_addc_u32 s25, s21, 0
	global_load_dwordx4 v[60:63], v131, s[24:25] nt
	ds_read2_b32 v[134:135], v129 offset0:0 offset1:65
	ds_read2_b32 v[136:137], v129 offset0:130 offset1:195
	ds_read2_b32 v[138:139], v130 offset0:4 offset1:69
	ds_read2_b32 v[140:141], v130 offset0:134 offset1:199
	ds_read2_b32 v[148:149], v129 offset0:8 offset1:73
	ds_read2_b32 v[150:151], v129 offset0:138 offset1:203
	ds_read2_b32 v[152:153], v130 offset0:12 offset1:77
	ds_read2_b32 v[154:155], v130 offset0:142 offset1:207
	s_mov_b64 s[24:25], s[22:23]
	s_waitcnt lgkmcnt(4)
; #define LAS __attribute__((address_space(3)))
; __device__ __forceinline__ unsigned pk2(float lo, float hi) { return pg8::cvt_pk_bf16(lo, hi); }
; __device__ __forceinline__ void p0_load(const float* W, int N, int k0, int n0, int lane, f32x4 (&v)[16]) {
;     const int c = lane & 15, rq = lane >> 4;
;     int col = n0 + 4 * c; col = col < N - 4 ? col : N - 4;
;     const float* p = W + (size_t)(k0 + rq) * N + col;
; #pragma unroll
;     for (int j = 0; j < 16; ++j) v[j] = __builtin_nontemporal_load((const f32x4*)(p + (size_t)(4 * j) * N));
; }
; __device__ __forceinline__ void p0_finish(bf16* WT, const float* gain, int N, int k0, int n0, int ldw, int blk, int off, int lane, const f32x4 (&v)[16], LAS float* scr) {
;     const int c = lane & 15, rq = lane >> 4, c8 = lane & 7;
;     f32x4 g0 = {1.f, 1.f, 1.f, 1.f}, g1 = g0;
;     if (gain) { g0 = *(const f32x4*)(gain + k0 + 8 * c8); g1 = *(const f32x4*)(gain + k0 + 8 * c8 + 4); }
; #pragma unroll
;     for (int j = 0; j < 16; ++j) { LAS float* s = scr + (4 * j + rq) * 65 + 4 * c; s[0] = v[j][0]; s[1] = v[j][1]; s[2] = v[j][2]; s[3] = v[j][3]; }
;     asm volatile("s_waitcnt lgkmcnt(0)" ::: "memory");
; #pragma unroll
;     for (int jj = 0; jj < 8; ++jj) { const int n = (lane >> 3) + 8 * jj; const LAS float* s = scr + (8 * c8) * 65 + n;
;         u32x4 o; o.x = pk2(s[0 * 65] * g0[0], s[1 * 65] * g0[1]); o.y = pk2(s[2 * 65] * g0[2], s[3 * 65] * g0[3]); o.z = pk2(s[4 * 65] * g1[0], s[5 * 65] * g1[1]); o.w = pk2(s[6 * 65] * g1[2], s[7 * 65] * g1[3]);
;         const int ng = n0 + n;
;         if (ng < N) { const int row = (ng >> 7) * blk + (ng & 127) + off; __builtin_nontemporal_store(o, (u32x4*)(WT + (size_t)row * ldw + k0 + 8 * c8)); } }
;     asm volatile("s_waitcnt lgkmcnt(0)" ::: "memory");
; }
	v_cvt_pk_bf16_f32 v142, v134, v135
	v_cvt_pk_bf16_f32 v143, v136, v137
	v_cvt_pk_bf16_f32 v144, v138, v139
	v_cvt_pk_bf16_f32 v145, v140, v141
	global_store_dwordx4 v132, v[142:145], s[24:25] nt
	ds_read2_b32 v[134:135], v129 offset0:16 offset1:81
	ds_read2_b32 v[136:137], v129 offset0:146 offset1:211
	ds_read2_b32 v[138:139], v130 offset0:20 offset1:85
	ds_read2_b32 v[140:141], v130 offset0:150 offset1:215
	s_add_u32 s24, s22, 0x2b400
	s_addc_u32 s25, s23, 0
	s_waitcnt lgkmcnt(4)
	v_cvt_pk_bf16_f32 v156, v148, v149
	v_cvt_pk_bf16_f32 v157, v150, v151
	v_cvt_pk_bf16_f32 v158, v152, v153
	v_cvt_pk_bf16_f32 v159, v154, v155
	global_store_dwordx4 v132, v[156:159], s[24:25] nt
	ds_read2_b32 v[148:149], v129 offset0:24 offset1:89
	ds_read2_b32 v[150:151], v129 offset0:154 offset1:219
	ds_read2_b32 v[152:153], v130 offset0:28 offset1:93
	ds_read2_b32 v[154:155], v130 offset0:158 offset1:223
	s_add_u32 s24, s22, 0x56800
	s_addc_u32 s25, s23, 0
	s_waitcnt lgkmcnt(4)
	v_cvt_pk_bf16_f32 v142, v134, v135
	v_cvt_pk_bf16_f32 v143, v136, v137
	v_cvt_pk_bf16_f32 v144, v138, v139
	v_cvt_pk_bf16_f32 v145, v140, v141
	global_store_dwordx4 v132, v[142:145], s[24:25] nt
	ds_read2_b32 v[134:135], v129 offset0:32 offset1:97
	ds_read2_b32 v[136:137], v129 offset0:162 offset1:227
	ds_read2_b32 v[138:139], v130 offset0:36 offset1:101
	ds_read2_b32 v[140:141], v130 offset0:166 offset1:231
	s_add_u32 s24, s22, 0x81c00
	s_addc_u32 s25, s23, 0
	s_waitcnt lgkmcnt(4)
	v_cvt_pk_bf16_f32 v156, v148, v149
	v_cvt_pk_bf16_f32 v157, v150, v151
	v_cvt_pk_bf16_f32 v158, v152, v153
	v_cvt_pk_bf16_f32 v159, v154, v155
	global_store_dwordx4 v132, v[156:159], s[24:25] nt
	ds_read2_b32 v[148:149], v129 offset0:40 offset1:105
	ds_read2_b32 v[150:151], v129 offset0:170 offset1:235
	ds_read2_b32 v[152:153], v130 offset0:44 offset1:109
	ds_read2_b32 v[154:155], v130 offset0:174 offset1:239
	s_add_u32 s24, s22, 0xad000
	s_addc_u32 s25, s23, 0
	s_waitcnt lgkmcnt(4)
	v_cvt_pk_bf16_f32 v142, v134, v135
	v_cvt_pk_bf16_f32 v143, v136, v137
	v_cvt_pk_bf16_f32 v144, v138, v139
	v_cvt_pk_bf16_f32 v145, v140, v141
	global_store_dwordx4 v132, v[142:145], s[24:25] nt
	ds_read2_b32 v[134:135], v129 offset0:48 offset1:113
	ds_read2_b32 v[136:137], v129 offset0:178 offset1:243
	ds_read2_b32 v[138:139], v130 offset0:52 offset1:117
	ds_read2_b32 v[140:141], v130 offset0:182 offset1:247
	s_add_u32 s24, s22, 0xd8400
	s_addc_u32 s25, s23, 0
	s_waitcnt lgkmcnt(4)
	v_cvt_pk_bf16_f32 v156, v148, v149
	v_cvt_pk_bf16_f32 v157, v150, v151
	v_cvt_pk_bf16_f32 v158, v152, v153
	v_cvt_pk_bf16_f32 v159, v154, v155
	global_store_dwordx4 v132, v[156:159], s[24:25] nt
	ds_read2_b32 v[148:149], v129 offset0:56 offset1:121
	ds_read2_b32 v[150:151], v129 offset0:186 offset1:251
	ds_read2_b32 v[152:153], v130 offset0:60 offset1:125
	ds_read2_b32 v[154:155], v130 offset0:190 offset1:255
	s_add_u32 s24, s22, 0x103800
	s_addc_u32 s25, s23, 0
	s_waitcnt lgkmcnt(4)
	v_cvt_pk_bf16_f32 v142, v134, v135
	v_cvt_pk_bf16_f32 v143, v136, v137
	v_cvt_pk_bf16_f32 v144, v138, v139
	v_cvt_pk_bf16_f32 v145, v140, v141
	global_store_dwordx4 v132, v[142:145], s[24:25] nt
	s_add_u32 s24, s22, 0x12ec00
	s_addc_u32 s25, s23, 0
	s_waitcnt lgkmcnt(0)
	v_cvt_pk_bf16_f32 v156, v148, v149
	v_cvt_pk_bf16_f32 v157, v150, v151
	v_cvt_pk_bf16_f32 v158, v152, v153
	v_cvt_pk_bf16_f32 v159, v154, v155
	global_store_dwordx4 v132, v[156:159], s[24:25] nt
	s_add_u32 s22, s22, 0x400
	s_addc_u32 s23, s23, 0
	s_add_i32 s26, s26, 1
	s_cmp_ge_u32 s26, 20
	s_cbranch_scc1 .Lhn_fin
	s_cmp_eq_u32 s26, 1
	s_cbranch_scc0 .Lhn_w1
	s_waitcnt vmcnt(24)
.Lhn_w1:
	s_waitcnt vmcnt(32)
	ds_write2_b32 v128, v64, v65 offset1:1
	ds_write2_b32 v128, v66, v67 offset0:2 offset1:3
	v_add_u32_e32 v133, 0x410, v128
	ds_write2_b32 v133, v68, v69 offset1:1
	ds_write2_b32 v133, v70, v71 offset0:2 offset1:3
	v_add_u32_e32 v147, 0x820, v128
	ds_write2_b32 v147, v72, v73 offset1:1
	ds_write2_b32 v147, v74, v75 offset0:2 offset1:3
	v_add_u32_e32 v133, 0xc30, v128
	ds_write2_b32 v133, v76, v77 offset1:1
	ds_write2_b32 v133, v78, v79 offset0:2 offset1:3
	v_add_u32_e32 v147, 0x1040, v128
	ds_write2_b32 v147, v80, v81 offset1:1
	ds_write2_b32 v147, v82, v83 offset0:2 offset1:3
	v_add_u32_e32 v133, 0x1450, v128
	ds_write2_b32 v133, v84, v85 offset1:1
	ds_write2_b32 v133, v86, v87 offset0:2 offset1:3
	v_add_u32_e32 v147, 0x1860, v128
	ds_write2_b32 v147, v88, v89 offset1:1
	ds_write2_b32 v147, v90, v91 offset0:2 offset1:3
	v_add_u32_e32 v133, 0x1c70, v128
	ds_write2_b32 v133, v92, v93 offset1:1
	ds_write2_b32 v133, v94, v95 offset0:2 offset1:3
	v_add_u32_e32 v147, 0x2080, v128
	ds_write2_b32 v147, v96, v97 offset1:1
	ds_write2_b32 v147, v98, v99 offset0:2 offset1:3
	v_add_u32_e32 v133, 0x2490, v128
	ds_write2_b32 v133, v100, v101 offset1:1
	ds_write2_b32 v133, v102, v103 offset0:2 offset1:3
	v_add_u32_e32 v147, 0x28a0, v128
	ds_write2_b32 v147, v104, v105 offset1:1
	ds_write2_b32 v147, v106, v107 offset0:2 offset1:3
	v_add_u32_e32 v133, 0x2cb0, v128
	ds_write2_b32 v133, v108, v109 offset1:1
	ds_write2_b32 v133, v110, v111 offset0:2 offset1:3
	v_add_u32_e32 v147, 0x30c0, v128
	ds_write2_b32 v147, v112, v113 offset1:1
	ds_write2_b32 v147, v114, v115 offset0:2 offset1:3
	v_add_u32_e32 v133, 0x34d0, v128
	ds_write2_b32 v133, v116, v117 offset1:1
	ds_write2_b32 v133, v118, v119 offset0:2 offset1:3
	v_add_u32_e32 v147, 0x38e0, v128
	ds_write2_b32 v147, v120, v121 offset1:1
	ds_write2_b32 v147, v122, v123 offset0:2 offset1:3
	v_add_u32_e32 v133, 0x3cf0, v128
	ds_write2_b32 v133, v124, v125 offset1:1
	ds_write2_b32 v133, v126, v127 offset0:2 offset1:3
	s_waitcnt lgkmcnt(0)
; #define LAS __attribute__((address_space(3)))
; __device__ __forceinline__ unsigned pk2(float lo, float hi) { return pg8::cvt_pk_bf16(lo, hi); }
; __device__ __forceinline__ void p0_load(const float* W, int N, int k0, int n0, int lane, f32x4 (&v)[16]) {
;     const int c = lane & 15, rq = lane >> 4;
;     int col = n0 + 4 * c; col = col < N - 4 ? col : N - 4;
;     const float* p = W + (size_t)(k0 + rq) * N + col;
; #pragma unroll
;     for (int j = 0; j < 16; ++j) v[j] = __builtin_nontemporal_load((const f32x4*)(p + (size_t)(4 * j) * N));
; }
; __device__ __forceinline__ void p0_finish(bf16* WT, const float* gain, int N, int k0, int n0, int ldw, int blk, int off, int lane, const f32x4 (&v)[16], LAS float* scr) {
;     const int c = lane & 15, rq = lane >> 4, c8 = lane & 7;
;     f32x4 g0 = {1.f, 1.f, 1.f, 1.f}, g1 = g0;
;     if (gain) { g0 = *(const f32x4*)(gain + k0 + 8 * c8); g1 = *(const f32x4*)(gain + k0 + 8 * c8 + 4); }
; #pragma unroll
;     for (int j = 0; j < 16; ++j) { LAS float* s = scr + (4 * j + rq) * 65 + 4 * c; s[0] = v[j][0]; s[1] = v[j][1]; s[2] = v[j][2]; s[3] = v[j][3]; }
;     asm volatile("s_waitcnt lgkmcnt(0)" ::: "memory");
; #pragma unroll
;     for (int jj = 0; jj < 8; ++jj) { const int n = (lane >> 3) + 8 * jj; const LAS float* s = scr + (8 * c8) * 65 + n;
;         u32x4 o; o.x = pk2(s[0 * 65] * g0[0], s[1 * 65] * g0[1]); o.y = pk2(s[2 * 65] * g0[2], s[3 * 65] * g0[3]); o.z = pk2(s[4 * 65] * g1[0], s[5 * 65] * g1[1]); o.w = pk2(s[6 * 65] * g1[2], s[7 * 65] * g1[3]);
;         const int ng = n0 + n;
;         if (ng < N) { const int row = (ng >> 7) * blk + (ng & 127) + off; __builtin_nontemporal_store(o, (u32x4*)(WT + (size_t)row * ldw + k0 + 8 * c8)); } }
;     asm volatile("s_waitcnt lgkmcnt(0)" ::: "memory");
; }
	s_cmp_lt_u32 s27, 20
	s_cselect_b32 s2, 0x800000, 0
	s_add_u32 s20, s20, s2
	s_addc_u32 s21, s21, 0
	s_add_i32 s27, s27, 1
	global_load_dwordx4 v[64:67], v131, s[20:21] nt
	s_add_u32 s24, s20, 0x10000
	s_addc_u32 s25, s21, 0
	global_load_dwordx4 v[68:71], v131, s[24:25] nt
	s_add_u32 s24, s20, 0x20000
	s_addc_u32 s25, s21, 0
	global_load_dwordx4 v[72:75], v131, s[24:25] nt
	s_add_u32 s24, s20, 0x30000
	s_addc_u32 s25, s21, 0
	global_load_dwordx4 v[76:79], v131, s[24:25] nt
	s_add_u32 s24, s20, 0x40000
	s_addc_u32 s25, s21, 0
	global_load_dwordx4 v[80:83], v131, s[24:25] nt
	s_add_u32 s24, s20, 0x50000
	s_addc_u32 s25, s21, 0
	global_load_dwordx4 v[84:87], v131, s[24:25] nt
	s_add_u32 s24, s20, 0x60000
	s_addc_u32 s25, s21, 0
	global_load_dwordx4 v[88:91], v131, s[24:25] nt
	s_add_u32 s24, s20, 0x70000
	s_addc_u32 s25, s21, 0
	global_load_dwordx4 v[92:95], v131, s[24:25] nt
	s_add_u32 s24, s20, 0x80000
	s_addc_u32 s25, s21, 0
	global_load_dwordx4 v[96:99], v131, s[24:25] nt
	s_add_u32 s24, s20, 0x90000
	s_addc_u32 s25, s21, 0
	global_load_dwordx4 v[100:103], v131, s[24:25] nt
	s_add_u32 s24, s20, 0xa0000
	s_addc_u32 s25, s21, 0
	global_load_dwordx4 v[104:107], v131, s[24:25] nt
	s_add_u32 s24, s20, 0xb0000
	s_addc_u32 s25, s21, 0
	global_load_dwordx4 v[108:111], v131, s[24:25] nt
	s_add_u32 s24, s20, 0xc0000
	s_addc_u32 s25, s21, 0
	global_load_dwordx4 v[112:115], v131, s[24:25] nt
	s_add_u32 s24, s20, 0xd0000
	s_addc_u32 s25, s21, 0
	global_load_dwordx4 v[116:119], v131, s[24:25] nt
	s_add_u32 s24, s20, 0xe0000
	s_addc_u32 s25, s21, 0
	global_load_dwordx4 v[120:123], v131, s[24:25] nt
	s_add_u32 s24, s20, 0xf0000
	s_addc_u32 s25, s21, 0
	global_load_dwordx4 v[124:127], v131, s[24:25] nt
	ds_read2_b32 v[134:135], v129 offset0:0 offset1:65
	ds_read2_b32 v[136:137], v129 offset0:130 offset1:195
	ds_read2_b32 v[138:139], v130 offset0:4 offset1:69
	ds_read2_b32 v[140:141], v130 offset0:134 offset1:199
	ds_read2_b32 v[148:149], v129 offset0:8 offset1:73
	ds_read2_b32 v[150:151], v129 offset0:138 offset1:203
	ds_read2_b32 v[152:153], v130 offset0:12 offset1:77
	ds_read2_b32 v[154:155], v130 offset0:142 offset1:207
	s_mov_b64 s[24:25], s[22:23]
	s_waitcnt lgkmcnt(4)
	v_cvt_pk_bf16_f32 v142, v134, v135
	v_cvt_pk_bf16_f32 v143, v136, v137
	v_cvt_pk_bf16_f32 v144, v138, v139
	v_cvt_pk_bf16_f32 v145, v140, v141
	global_store_dwordx4 v132, v[142:145], s[24:25] nt
	ds_read2_b32 v[134:135], v129 offset0:16 offset1:81
	ds_read2_b32 v[136:137], v129 offset0:146 offset1:211
	ds_read2_b32 v[138:139], v130 offset0:20 offset1:85
	ds_read2_b32 v[140:141], v130 offset0:150 offset1:215
	s_add_u32 s24, s22, 0x2b400
	s_addc_u32 s25, s23, 0
	s_waitcnt lgkmcnt(4)
	v_cvt_pk_bf16_f32 v156, v148, v149
	v_cvt_pk_bf16_f32 v157, v150, v151
	v_cvt_pk_bf16_f32 v158, v152, v153
	v_cvt_pk_bf16_f32 v159, v154, v155
	global_store_dwordx4 v132, v[156:159], s[24:25] nt
	ds_read2_b32 v[148:149], v129 offset0:24 offset1:89
	ds_read2_b32 v[150:151], v129 offset0:154 offset1:219
	ds_read2_b32 v[152:153], v130 offset0:28 offset1:93
	ds_read2_b32 v[154:155], v130 offset0:158 offset1:223
	s_add_u32 s24, s22, 0x56800
	s_addc_u32 s25, s23, 0
	s_waitcnt lgkmcnt(4)
	v_cvt_pk_bf16_f32 v142, v134, v135
	v_cvt_pk_bf16_f32 v143, v136, v137
	v_cvt_pk_bf16_f32 v144, v138, v139
	v_cvt_pk_bf16_f32 v145, v140, v141
	global_store_dwordx4 v132, v[142:145], s[24:25] nt
	ds_read2_b32 v[134:135], v129 offset0:32 offset1:97
	ds_read2_b32 v[136:137], v129 offset0:162 offset1:227
	ds_read2_b32 v[138:139], v130 offset0:36 offset1:101
	ds_read2_b32 v[140:141], v130 offset0:166 offset1:231
	s_add_u32 s24, s22, 0x81c00
	s_addc_u32 s25, s23, 0
	s_waitcnt lgkmcnt(4)
	v_cvt_pk_bf16_f32 v156, v148, v149
	v_cvt_pk_bf16_f32 v157, v150, v151
	v_cvt_pk_bf16_f32 v158, v152, v153
	v_cvt_pk_bf16_f32 v159, v154, v155
	global_store_dwordx4 v132, v[156:159], s[24:25] nt
	ds_read2_b32 v[148:149], v129 offset0:40 offset1:105
	ds_read2_b32 v[150:151], v129 offset0:170 offset1:235
	ds_read2_b32 v[152:153], v130 offset0:44 offset1:109
	ds_read2_b32 v[154:155], v130 offset0:174 offset1:239
	s_add_u32 s24, s22, 0xad000
	s_addc_u32 s25, s23, 0
	s_waitcnt lgkmcnt(4)
	v_cvt_pk_bf16_f32 v142, v134, v135
	v_cvt_pk_bf16_f32 v143, v136, v137
	v_cvt_pk_bf16_f32 v144, v138, v139
	v_cvt_pk_bf16_f32 v145, v140, v141
	global_store_dwordx4 v132, v[142:145], s[24:25] nt
	ds_read2_b32 v[134:135], v129 offset0:48 offset1:113
	ds_read2_b32 v[136:137], v129 offset0:178 offset1:243
	ds_read2_b32 v[138:139], v130 offset0:52 offset1:117
	ds_read2_b32 v[140:141], v130 offset0:182 offset1:247
	s_add_u32 s24, s22, 0xd8400
	s_addc_u32 s25, s23, 0
	s_waitcnt lgkmcnt(4)
	v_cvt_pk_bf16_f32 v156, v148, v149
	v_cvt_pk_bf16_f32 v157, v150, v151
	v_cvt_pk_bf16_f32 v158, v152, v153
	v_cvt_pk_bf16_f32 v159, v154, v155
	global_store_dwordx4 v132, v[156:159], s[24:25] nt
	ds_read2_b32 v[148:149], v129 offset0:56 offset1:121
	ds_read2_b32 v[150:151], v129 offset0:186 offset1:251
	ds_read2_b32 v[152:153], v130 offset0:60 offset1:125
	ds_read2_b32 v[154:155], v130 offset0:190 offset1:255
	s_add_u32 s24, s22, 0x103800
	s_addc_u32 s25, s23, 0
	s_waitcnt lgkmcnt(4)
	v_cvt_pk_bf16_f32 v142, v134, v135
	v_cvt_pk_bf16_f32 v143, v136, v137
	v_cvt_pk_bf16_f32 v144, v138, v139
	v_cvt_pk_bf16_f32 v145, v140, v141
	global_store_dwordx4 v132, v[142:145], s[24:25] nt
	s_add_u32 s24, s22, 0x12ec00
	s_addc_u32 s25, s23, 0
	s_waitcnt lgkmcnt(0)
	v_cvt_pk_bf16_f32 v156, v148, v149
	v_cvt_pk_bf16_f32 v157, v150, v151
	v_cvt_pk_bf16_f32 v158, v152, v153
	v_cvt_pk_bf16_f32 v159, v154, v155
	global_store_dwordx4 v132, v[156:159], s[24:25] nt
	s_add_u32 s22, s22, 0x400
	s_addc_u32 s23, s23, 0
	s_add_i32 s26, s26, 1
	s_cmp_lt_u32 s26, 20
	s_cbranch_scc1 .Lhn_loop
